# v022 with waves 4-7 (state waves) prioritised during the HGRN2 seqpass phase only
# baseline (speedup 1.0000x reference)
.LBB0_833:
	s_or_b64 exec, exec, s[8:9]
	s_waitcnt lgkmcnt(0)
	v_mov_b32_e32 v0, v184
	s_barrier
	s_setprio 0
	s_cmp_lt_u32 s99, 0x100
	s_cbranch_scc1 .Lsq_in
	s_setprio 1
.Lsq_in:
	s_cmpk_gt_i32 s2, 0xff
	v_readfirstlane_b32 s4, v0
	s_cbranch_scc1 .LBB0_856
	s_ashr_i32 s5, s4, 6
	v_lshlrev_b32_e32 v5, 4, v0
	v_lshlrev_b32_e32 v4, 11, v0
	v_and_b32_e32 v5, 0xf0, v5
	s_mov_b32 s6, 0x18000
	s_cmp_gt_i32 s5, 3
	v_and_or_b32 v128, v4, s6, v5
	s_movk_i32 s6, 0x1100
	s_cselect_b64 s[10:11], -1, 0
	s_add_i32 s18, s5, -4
	v_cmp_gt_i32_e64 s[8:9], s6, v0
	v_sub_co_u32_e64 v160, s[6:7], s5, 6
	s_mov_b32 s15, 0
	s_lshl_b32 s14, s18, 3
	s_xor_b64 s[12:13], s[6:7], -1
	s_lshl_b32 s6, s5, 12
	s_lshl_b64 s[16:17], s[14:15], 17
	s_lshl_b32 s14, s18, 5
	s_add_i32 s26, s6, 0
	s_lshl_b64 s[6:7], s[14:15], 6
	s_add_u32 s27, s70, s6
	s_addc_u32 s28, s71, s7
	s_lshl_b32 s14, s18, 11
	s_lshl_b32 s20, s5, 2
	s_lshl_b32 s22, s5, 5
	s_add_i32 s29, s14, 0
	s_lshl_b32 s14, s18, 12
	s_ashr_i32 s21, s20, 31
	s_ashr_i32 s23, s22, 31
	v_and_b32_e32 v1, 63, v0
	s_add_i32 s14, s14, 0
	s_lshl_b64 s[18:19], s[20:21], 17
	s_lshl_b64 s[22:23], s[22:23], 2
	v_lshlrev_b32_e32 v130, 4, v1
	s_add_u32 s24, s74, s22
	v_bfe_u32 v2, v0, 5, 1
	v_and_b32_e32 v3, 31, v0
	v_lshlrev_b32_e32 v1, 12, v160
	v_add_u32_e32 v163, s14, v130
	s_movk_i32 s14, 0x110
	s_addc_u32 s25, s75, s23
	s_andn2_b32 s4, s4, 63
	v_mov_b32_e32 v133, 0
	v_add_u32_e32 v4, 0, v1
	v_lshlrev_b32_e32 v132, 4, v2
	v_lshl_add_u32 v6, v2, 8, s29
	v_mad_u32_u24 v1, v3, s14, 0
	v_lshl_or_b32 v2, v2, 3, s4
	v_mov_b32_e32 v131, v133
	v_lshlrev_b32_e32 v5, 1, v3
	v_add_u32_e32 v164, v1, v132
	v_add_u32_e32 v165, v1, v2
	v_add_u32_e32 v166, 0xfffffe00, v0
	v_lshl_add_u32 v167, v0, 2, 0
	v_or_b32_e32 v0, s22, v132
	v_mov_b32_e32 v1, s23
	s_mov_b64 s[4:5], 0x4000640
	v_lshlrev_b32_e32 v161, 2, v160
	v_lshl_add_u64 v[134:135], s[58:59], 0, v[130:131]
	v_mov_b32_e32 v129, v133
	s_waitcnt vmcnt(7)
	v_add_u32_e32 v162, 0, v130
	v_lshl_add_u64 v[136:137], s[24:25], 0, v[132:133]
	s_sub_i32 s30, s20, 24
	v_or_b32_e32 v138, s16, v128
	v_mov_b32_e32 v139, s17
	v_or_b32_e32 v140, s6, v130
	v_mov_b32_e32 v141, s7
	v_or_b32_e32 v142, s18, v128
	v_mov_b32_e32 v143, s19
	v_lshl_add_u64 v[144:145], v[0:1], 0, s[4:5]
	s_movk_i32 s31, 0x4000
	s_mov_b32 s34, 0x24000
	s_mov_b32 s35, 0x44000
	s_mov_b32 s36, 0x64000
	s_mov_b32 s37, 0x204000
	s_mov_b32 s38, 0x224000
	s_mov_b32 s39, 0x244000
	s_mov_b32 s40, 0x264000
	s_mov_b32 s41, 0x18e48000
	s_mov_b32 s42, 0x18e68000
	s_mov_b32 s43, 0x18e88000
	s_mov_b32 s44, 0x18ea8000
	s_mov_b32 s45, 0x19048000
	s_mov_b32 s46, 0x19068000
	s_mov_b32 s47, 0x19088000
	s_mov_b32 s48, 0x190a8000
	s_mov_b64 s[20:21], 0x600000
	s_mov_b32 s49, 0x20000
	s_mov_b32 s50, 0x40000
	s_mov_b32 s51, 0x60000
	s_mov_b32 s52, 0x200000
	s_mov_b32 s53, 0x220000
	s_mov_b32 s61, 0x240000
	s_mov_b32 s74, 0x260000
	s_mov_b32 s75, 0x18c44000
	s_mov_b32 s76, 0x18c64000
	s_mov_b32 s77, 0x18c84000
	s_mov_b32 s78, 0x18ca4000
	s_mov_b32 s79, 0x18e44000
	s_mov_b32 s80, 0x18e64000
	s_mov_b32 s81, 0x18e84000
	s_mov_b32 s82, 0x18ea4000
	s_mov_b32 s83, 0x19044000
	s_mov_b32 s84, 0x19064000
	s_mov_b32 s85, 0x19084000
	s_mov_b32 s86, 0x190a4000
	v_add_u32_e32 v168, v4, v130
	v_add_u32_e32 v169, v6, v5
	s_mov_b32 s87, s2
	s_branch .LBB0_836

.LBB0_908:
	s_or_b64 exec, exec, s[8:9]
	s_waitcnt lgkmcnt(0)
	v_cvt_f32_u32_e32 v0, s64
	s_sub_i32 s3, 0, s64
	v_mov_b32_e32 v8, v184
	s_mov_b32 s17, 0
	v_rcp_iflag_f32_e32 v0, v0
	s_barrier
	s_setprio 0
	s_cmp_gt_u32 s99, 0xff
	s_cbranch_scc1 .Lsq_out
	s_setprio 1
.Lsq_out:
	v_mul_f32_e32 v0, 0x4f7ffffe, v0
	v_cvt_u32_f32_e32 v0, v0
	s_nop 0
	v_readfirstlane_b32 s4, v0
	s_mul_i32 s3, s3, s4
	s_mul_hi_u32 s3, s4, s3
	s_add_i32 s4, s4, s3
	s_lshr_b32 s3, s4, 18
	s_mul_i32 s4, s3, s64
	s_sub_i32 s4, 0x4000, s4
	s_add_i32 s5, s3, 1
	s_sub_i32 s6, s4, s64
	s_cmp_ge_u32 s4, s64
	s_cselect_b32 s3, s5, s3
	s_cselect_b32 s4, s6, s4
	s_add_i32 s5, s3, 1
	s_cmp_ge_u32 s4, s64
	s_cselect_b32 s3, s5, s3
	s_mul_i32 s18, s3, s2
	s_add_i32 s3, s18, s3
	s_cmp_ge_u32 s18, s3
	s_movk_i32 s4, 0x4000
	s_cbranch_scc1 .LBB0_911
	s_load_dwordx2 s[6:7], s[0:1], 0x58
	v_and_b32_e32 v0, 15, v8
	v_lshlrev_b32_e32 v9, 5, v0
	v_mbcnt_lo_u32_b32 v11, -1, 0
	v_mbcnt_hi_u32_b32 v11, -1, v11
	s_waitcnt lgkmcnt(0)
	global_load_dwordx4 v[0:3], v9, s[6:7]
	global_load_dwordx4 v[4:7], v9, s[6:7] offset:16
	v_and_b32_e32 v13, 64, v11
	v_xor_b32_e32 v12, 1, v11
	v_add_u32_e32 v13, 64, v13
	v_cmp_lt_i32_e32 vcc, v12, v13
	s_add_i32 s6, s18, 1
	s_lshl_b32 s5, s18, 5
	v_cndmask_b32_e32 v12, v11, v12, vcc
	v_lshlrev_b32_e32 v38, 2, v12
	v_xor_b32_e32 v12, 2, v11
	v_cmp_lt_i32_e32 vcc, v12, v13
	s_ashr_i32 s7, s6, 31
	s_addk_i32 s5, 0x60
	v_cndmask_b32_e32 v12, v11, v12, vcc
	v_lshlrev_b32_e32 v39, 2, v12
	v_xor_b32_e32 v12, 4, v11
	v_cmp_lt_i32_e32 vcc, v12, v13
	s_lshl_b64 s[6:7], s[6:7], 15
	s_add_u32 s20, s58, s6
	v_cndmask_b32_e32 v12, v11, v12, vcc
	v_lshlrev_b32_e32 v40, 2, v12
	v_xor_b32_e32 v12, 8, v11
	s_addc_u32 s21, s59, s7
	s_ashr_i32 s19, s18, 31
	v_ashrrev_i32_e32 v36, 4, v8
	v_bfe_u32 v37, v8, 2, 2
	v_lshlrev_b32_e32 v8, 3, v8
	v_cmp_lt_i32_e32 vcc, v12, v13
	s_lshl_b64 s[6:7], s[18:19], 15
	v_and_b32_e32 v10, 24, v8
	v_ashrrev_i32_e32 v9, 31, v8
	v_cndmask_b32_e32 v11, v11, v12, vcc
	s_add_u32 s22, s58, s6
	s_waitcnt vmcnt(3)
	v_mov_b32_e32 v25, 0
	v_lshlrev_b32_e32 v41, 2, v11
	v_lshlrev_b64 v[26:27], 1, v[8:9]
	s_addc_u32 s23, s59, s7
	v_lshlrev_b32_e32 v24, 1, v10
	s_mov_b32 s6, 0x1884a000
	s_movk_i32 s7, 0x6000
	v_mov_b32_e32 v42, 0x358637bd
	s_mov_b32 s19, 0xf800000
	v_mov_b32_e32 v43, 0x260
	s_mov_b32 s24, 0x18848000
